# B (MLA) units: static s_setprio 1 for waves 0-3 like the GQA units
# speedup vs baseline: 1.0009x; 1.0009x over previous
; #define PHON(k) constexpr (((MK_PHMASK) >> (k)) & 1)
; __global__ void __launch_bounds__(512, 2) mega_fwd(Args args) {
;     ...
;             if PHON(7) for (int u = bid; u < 256; u += G) { const int xq = u & 7, hd = xq & 3, qb = (u >> 3) + 32 * (xq >> 2), q0 = qb * 256;
;                 { const float sc = 0.07216878364870322f;
;                   if (wave0 < 4) att::attn_unit<12, 0, 0, 1, 4, 1, 0>(QB + (size_t)q0 * 768 + hd * 192, 768, KVB + hd * 256, 1024, KPE, 64, KVB + hd * 256 + 128, 1024,
;                                             0, S, q0, nullptr, 0.f, 0.f, MIX + (size_t)q0 * DM + 512 + hd * 128, DM, nullptr, 0.f, nullptr, 0.f, (char*)lds, wave0, COS, SIN); else att::attn_unit<12, 0, 0, 1, 4, 1, 1>(QB + (size_t)q0 * 768 + hd * 192, 768, KVB + hd * 256, 1024, KPE, 64, KVB + hd * 256 + 128, 1024,
;                                             0, S, q0, nullptr, 0.f, 0.f, MIX + (size_t)q0 * DM + 512 + hd * 128, DM, nullptr, 0.f, nullptr, 0.f, (char*)lds, wave0, COS, SIN); }
;             }
;             if (wave0 < 4) __builtin_amdgcn_s_setprio(1);
.LBB0_355:
	v_readlane_b32 s6, v254, 17
	v_readlane_b32 s7, v254, 18
	s_nop 4
	s_and_b64 vcc, exec, s[6:7]
	s_cbranch_vccz .Lmy_B_noprio
	s_setprio 1
